# v20_kswz
# speedup vs baseline: 1.0119x; 1.0068x over previous
; DEVI void moba_item(const Params& p, int l, int item) {
;     ...
;   bf16x8 qb[4];
; #pragma unroll
;   for (int ks = 0; ks < 4; ++ks) qb[ks] = *(const bf16x8*)(Qs + (w * 16 + fr) * 136 + ks * 32 + fq * 8);
; #pragma unroll
;   for (int i = 0; i < 4; ++i) {
;     *(bf16x8*)(Kb0 + (kkey + 32 * i) * 136 + kdg * 8) = pk_[i];
;     *(bf16x8*)(Vb0 + (kkey + 32 * i) * 144 + kdg * 8) = pv_[i];
;   }
;   __syncthreads();
;   unsigned pend = selm[128];
;   const unsigned mysel = selm[w * 16 + fr];
;   __syncthreads();
;   float m = -INFINITY, lsum = 0.f;
;   f32x4 oacc[8];
; #pragma unroll
;   for (int ct = 0; ct < 8; ++ct) oacc[ct] = f32x4{0.f, 0.f, 0.f, 0.f};
;   const int qinb = (qt & 1) * 128 + w * 16 + fr;
;   int cblk = qblk, chalf = 0;
;   int nblk, nhalf;
;     ...
;   MOBA_NEXT(cblk, chalf, nblk, nhalf);
;   if (nblk >= 0) MOBA_LOAD(nblk, nhalf);
;   int par = 0;
.LBB0_653:
	s_or_b64 exec, exec, s[2:3]
	s_waitcnt vmcnt(0)
	v_lshrrev_b32_e32 v32, 2, v48
	v_and_b32_e32 v51, 0x70, v32
	v_lshlrev_b32_e32 v52, 3, v50
	v_and_b32_e32 v49, 3, v154
	v_or_b32_e32 v156, v51, v50
	v_mul_u32_u24_e32 v32, 0x110, v156
	v_lshlrev_b32_e32 v33, 4, v49
	v_lshl_add_u32 v53, v52, 1, 0
	v_add3_u32 v44, s70, v32, v33
	v_and_b32_e32 v199, 15, v154
	v_add_u32_e32 v199, 4, v199
	v_bfe_u32 v199, v199, 3, 1
	v_xor_b32_e32 v199, v199, v50
	v_lshlrev_b32_e32 v199, 4, v199
	v_add_u32_e32 v54, v199, v155
	v_mad_u32_u24 v53, v154, s75, v53
	v_or_b32_e32 v200, s27, v156
	v_mov_b64_e32 v[196:197], s[92:93]
	v_lshlrev_b32_e32 v198, 3, v49
	v_mad_u64_u32 v[196:197], s[10:11], v200, s97, v[196:197]
	v_lshl_add_u64 v[196:197], v[196:197], 0, s[98:99]
	v_add_co_u32_e32 v196, vcc, v198, v196
	s_nop 1
	v_addc_co_u32_e32 v197, vcc, 0, v197, vcc
	v_add_co_u32_e32 v196, vcc, 0x4200, v196
	s_nop 1
	v_addc_co_u32_e32 v197, vcc, 0, v197, vcc
	global_load_dwordx2 v[180:181], v[196:197], off
	global_load_dwordx2 v[182:183], v[196:197], off offset:32
	global_load_dwordx2 v[184:185], v[196:197], off offset:64
	global_load_dwordx2 v[186:187], v[196:197], off offset:96
	global_load_dwordx2 v[188:189], v[196:197], off offset:128
	global_load_dwordx2 v[190:191], v[196:197], off offset:160
	global_load_dwordx2 v[192:193], v[196:197], off offset:192
	global_load_dwordx2 v[194:195], v[196:197], off offset:224
	ds_read_b128 v[32:35], v44
	ds_read_b128 v[36:39], v44 offset:64
	ds_read_b128 v[40:43], v44 offset:128
	ds_read_b128 v[44:47], v44 offset:192
	ds_write_b128 v54, v[0:3]
	ds_write_b128 v53, v[4:7] offset:34816
	ds_write_b128 v54, v[8:11] offset:8704
	ds_write_b128 v53, v[12:15] offset:44032
	ds_write_b128 v54, v[16:19] offset:17408
	ds_write_b128 v53, v[20:23] offset:53248
	ds_write_b128 v54, v[24:27] offset:26112
	ds_write_b128 v53, v[28:31] offset:62464
	v_mov_b32_e32 v53, s73
	s_waitcnt lgkmcnt(0)
	s_barrier
	ds_read_b32 v53, v53
	s_and_b32 s8, s20, 1
	v_lshl_add_u32 v54, v156, 2, 0
	s_lshl_b32 s3, s8, 7
	v_add_u32_e32 v54, 0x1e200, v54
	s_waitcnt lgkmcnt(0)
	v_readfirstlane_b32 s2, v53
	v_subrev_co_u32_e32 v53, vcc, 1, v53
	s_ff1_i32_b32 s9, s2
	s_and_b64 s[6:7], vcc, exec
	ds_read_b32 v157, v54
	s_cselect_b32 s7, -1, s9
	s_cmp_eq_u32 s8, 0
	s_cselect_b64 s[8:9], -1, 0
	s_and_b64 s[10:11], s[8:9], exec
	s_cselect_b32 s34, s7, s28
	v_readfirstlane_b32 s6, v53
	s_cmp_lt_i32 s34, 0
	v_lshlrev_b32_e32 v210, 1, v52
	s_waitcnt lgkmcnt(0)
	s_barrier
	s_cbranch_scc1 .LBB0_655
	s_lshl_b32 s7, s34, 8
	s_add_i32 s7, s7, s29
	s_or_b32 s7, s7, s3
	v_or_b32_e32 v26, s7, v154
	v_mov_b64_e32 v[24:25], s[92:93]
	v_mad_u64_u32 v[0:1], s[10:11], v26, s97, v[24:25]
	v_lshl_add_u64 v[0:1], v[0:1], 0, s[98:99]
	v_or_b32_e32 v8, 32, v26
	v_lshl_add_u64 v[0:1], v[0:1], 0, v[210:211]
	v_mad_u64_u32 v[8:9], s[10:11], v8, s97, v[24:25]
	v_add_co_u32_e32 v4, vcc, 0x3000, v0
	v_lshl_add_u64 v[8:9], v[8:9], 0, s[98:99]
	v_or_b32_e32 v16, 64, v26
	v_addc_co_u32_e32 v5, vcc, 0, v1, vcc
	v_lshl_add_u64 v[8:9], v[8:9], 0, v[210:211]
	v_mad_u64_u32 v[16:17], s[10:11], v16, s97, v[24:25]
	v_add_co_u32_e32 v12, vcc, 0x3000, v8
	v_lshl_add_u64 v[16:17], v[16:17], 0, s[98:99]
	v_or_b32_e32 v26, 0x60, v26
	v_addc_co_u32_e32 v13, vcc, 0, v9, vcc
	v_lshl_add_u64 v[16:17], v[16:17], 0, v[210:211]
	v_mad_u64_u32 v[24:25], s[10:11], v26, s97, v[24:25]
	v_add_co_u32_e32 v20, vcc, 0x3000, v16
	v_lshl_add_u64 v[24:25], v[24:25], 0, s[98:99]
	s_nop 0
	v_addc_co_u32_e32 v21, vcc, 0, v17, vcc
	v_lshl_add_u64 v[24:25], v[24:25], 0, v[210:211]
	v_add_co_u32_e32 v28, vcc, 0x3000, v24
	global_load_dwordx4 v[0:3], v[4:5], off offset:512
	s_nop 0
	global_load_dwordx4 v[4:7], v[4:5], off offset:2560
	v_addc_co_u32_e32 v29, vcc, 0, v25, vcc
	global_load_dwordx4 v[8:11], v[12:13], off offset:512
	s_nop 0
	global_load_dwordx4 v[12:15], v[12:13], off offset:2560
	s_nop 0
	global_load_dwordx4 v[16:19], v[20:21], off offset:512
	s_nop 0
	global_load_dwordx4 v[20:23], v[20:21], off offset:2560
	s_nop 0
	global_load_dwordx4 v[24:27], v[28:29], off offset:512
	s_nop 0
	global_load_dwordx4 v[28:31], v[28:29], off offset:2560
.LBB0_655:
	v_or_b32_e32 v51, s3, v51
	v_or_b32_e32 v160, v51, v50
	s_and_b64 s[10:11], s[8:9], exec
	v_mul_u32_u24_e32 v161, 0x110, v50
	v_lshrrev_b32_e32 v50, 2, v50
	v_lshlrev_b32_e32 v158, 2, v49
	s_cselect_b32 s3, s6, -1
	v_and_b32_e32 v162, 48, v48
	v_and_b32_e32 v198, 15, v48
	v_add_u32_e32 v198, 4, v198
	v_bfe_u32 v198, v198, 3, 1
	v_lshlrev_b32_e32 v198, 4, v198
	v_xor_b32_e32 v162, v162, v198
	v_or_b32_e32 v49, v158, v50
	v_lshlrev_b32_e32 v48, 2, v48
	v_mov_b32_e32 v166, 0
	v_mul_u32_u24_e32 v159, 0x120, v154
	s_and_b32 s30, s3, s2
	s_xor_b64 s[10:11], s[8:9], -1
	v_mul_u32_u24_e32 v163, 0x120, v49
	v_and_b32_e32 v164, 12, v48
	v_or_b32_e32 v165, 15, v51
	v_mov_b32_e32 v167, 0xff800000
	s_mov_b32 s31, 0
	v_mov_b32_e32 v168, 0
	s_mov_b32 s38, s28
	v_mov_b32_e32 v48, 0
	v_mov_b32_e32 v49, v166
	v_mov_b32_e32 v50, v166
	v_mov_b32_e32 v51, v166
	v_mov_b32_e32 v52, 0
	v_mov_b32_e32 v53, v166
	v_mov_b32_e32 v54, v166
	v_mov_b32_e32 v55, v166
	v_mov_b32_e32 v56, 0
	v_mov_b32_e32 v57, v166
	v_mov_b32_e32 v58, v166
	v_mov_b32_e32 v59, v166
	v_mov_b32_e32 v60, 0
	v_mov_b32_e32 v61, v166
	v_mov_b32_e32 v62, v166
	v_mov_b32_e32 v63, v166
	v_mov_b32_e32 v64, 0
	v_mov_b32_e32 v65, v166
	v_mov_b32_e32 v66, v166
	v_mov_b32_e32 v67, v166
	v_mov_b32_e32 v68, 0
	v_mov_b32_e32 v69, v166
	v_mov_b32_e32 v70, v166
	v_mov_b32_e32 v71, v166
	v_mov_b32_e32 v72, 0
	v_mov_b32_e32 v73, v166
	v_mov_b32_e32 v74, v166
	v_mov_b32_e32 v75, v166
	v_mov_b32_e32 v76, 0
	v_mov_b32_e32 v77, v166
	v_mov_b32_e32 v78, v166
	v_mov_b32_e32 v79, v166

; DEVI void moba_item(const Params& p, int l, int item) {
;     ...
;   while (cblk >= 0) {
;     u16* Kc = par ? Kb1 : Kb0; u16* Vc = par ? Vb1 : Vb0;
;     u16* Kn = par ? Kb0 : Kb1; u16* Vn = par ? Vb0 : Vb1;
;     int n2blk = -1, n2half = 0;
;     if (nblk >= 0) {
; #pragma unroll
;       for (int i = 0; i < 4; ++i) {
;         *(bf16x8*)(Kn + (kkey + 32 * i) * 136 + kdg * 8) = pk_[i];
;         *(bf16x8*)(Vn + (kkey + 32 * i) * 144 + kdg * 8) = pv_[i];
;       }
;       MOBA_NEXT(nblk, nhalf, n2blk, n2half);
;       if (n2blk >= 0) MOBA_LOAD(n2blk, n2half);
;     }
.LBB0_658:
	s_and_b64 s[6:7], s[2:3], exec
	s_cselect_b32 s6, s72, s78
	s_cselect_b32 s7, s70, 0
	s_cmp_eq_u32 s35, s28
	v_add3_u32 v80, s7, v199, v155
	v_add3_u32 v81, s6, v210, v159
	s_cselect_b64 s[6:7], -1, 0
	s_and_b64 s[6:7], s[8:9], s[6:7]
	s_waitcnt vmcnt(7)
	ds_write_b128 v80, v[0:3]
	s_waitcnt vmcnt(6)
	ds_write_b128 v81, v[4:7]
	s_waitcnt vmcnt(5)
	ds_write_b128 v80, v[8:11] offset:8704
	s_waitcnt vmcnt(4)
	ds_write_b128 v81, v[12:15] offset:9216
	s_waitcnt vmcnt(3)
	ds_write_b128 v80, v[16:19] offset:17408
	s_waitcnt vmcnt(2)
	ds_write_b128 v81, v[20:23] offset:18432
	s_waitcnt vmcnt(1)
	ds_write_b128 v80, v[24:27] offset:26112
	s_waitcnt vmcnt(0)
	ds_write_b128 v81, v[28:31] offset:27648
	s_or_b64 s[6:7], s[10:11], s[6:7]
	v_sub_co_u32_e64 v80, s[22:23], s30, 1
	s_ff1_i32_b32 s34, s30
	s_and_b64 s[22:23], s[22:23], exec
	s_cselect_b32 s34, -1, s34
	s_and_b64 s[22:23], s[6:7], exec
	v_readfirstlane_b32 s22, v80
	s_cselect_b32 s23, s34, s35
	s_cselect_b32 s22, s22, -1
	s_cmp_lt_i32 s23, 0
	s_mov_b32 s34, -1
	s_cbranch_scc1 .LBB0_660
	s_lshl_b32 s34, s23, 8
	s_add_i32 s34, s34, s29
	s_and_b64 s[36:37], s[6:7], exec
	s_cselect_b32 s36, 0, 0x80
	s_or_b32 s34, s34, s36
	v_or_b32_e32 v26, s34, v154
	v_mov_b64_e32 v[24:25], s[92:93]
	v_mad_u64_u32 v[0:1], s[36:37], v26, s97, v[24:25]
	v_lshl_add_u64 v[0:1], v[0:1], 0, s[98:99]
	v_or_b32_e32 v8, 32, v26
	v_lshl_add_u64 v[0:1], v[0:1], 0, v[210:211]
	v_mad_u64_u32 v[8:9], s[36:37], v8, s97, v[24:25]
	v_add_co_u32_e32 v4, vcc, s68, v0
	v_lshl_add_u64 v[8:9], v[8:9], 0, s[98:99]
	v_or_b32_e32 v16, 64, v26
	v_addc_co_u32_e32 v5, vcc, 0, v1, vcc
	v_lshl_add_u64 v[8:9], v[8:9], 0, v[210:211]
	v_mad_u64_u32 v[16:17], s[36:37], v16, s97, v[24:25]
	v_add_co_u32_e32 v12, vcc, s68, v8
	v_lshl_add_u64 v[16:17], v[16:17], 0, s[98:99]
	v_or_b32_e32 v26, 0x60, v26
	v_addc_co_u32_e32 v13, vcc, 0, v9, vcc
	v_lshl_add_u64 v[16:17], v[16:17], 0, v[210:211]
	v_mad_u64_u32 v[24:25], s[36:37], v26, s97, v[24:25]
	v_add_co_u32_e32 v20, vcc, s68, v16
	v_lshl_add_u64 v[24:25], v[24:25], 0, s[98:99]
	s_nop 0
	v_addc_co_u32_e32 v21, vcc, 0, v17, vcc
	v_lshl_add_u64 v[24:25], v[24:25], 0, v[210:211]
	v_add_co_u32_e32 v28, vcc, 0x3000, v24
	global_load_dwordx4 v[0:3], v[4:5], off offset:512
	s_nop 0
	global_load_dwordx4 v[4:7], v[4:5], off offset:2560
	v_addc_co_u32_e32 v29, vcc, 0, v25, vcc
	global_load_dwordx4 v[8:11], v[12:13], off offset:512
	s_nop 0
	global_load_dwordx4 v[12:15], v[12:13], off offset:2560
	s_nop 0
	global_load_dwordx4 v[16:19], v[20:21], off offset:512
	s_nop 0
	global_load_dwordx4 v[20:23], v[20:21], off offset:2560
	s_nop 0
	global_load_dwordx4 v[24:27], v[28:29], off offset:512
	s_nop 0
	global_load_dwordx4 v[28:31], v[28:29], off offset:2560
	s_mov_b32 s34, s23

; DEVI f32x4 mfma16(bf16x8 a, bf16x8 b, f32x4 c) { return __builtin_amdgcn_mfma_f32_16x16x32_bf16(a, b, c, 0, 0, 0); }
; DEVI float xq_max(float v) { v = fmaxf(v, __shfl_xor(v, 16)); v = fmaxf(v, __shfl_xor(v, 32)); return v; }
; template <bool OWN>
; DEVI void moba_half(const u16* Kt, const u16* Vs, const int kofs, const bf16x8 (&qb)[4], f32x4 (&oacc)[8], float& m, float& lsum,
;                     const bool lanesel, const int qinb, const int lane) {
;     ...
; #pragma unroll
;   for (int kp = 0; kp < 4; ++kp) {
;     bf16x8 kf[2][4];
; #pragma unroll
;     for (int t = 0; t < 2; ++t)
; #pragma unroll
;       for (int ks = 0; ks < 4; ++ks) kf[t][ks] = *(const bf16x8*)(kbase + (2 * kp + t) * 16 * 136 + ks * 32);
;     f32x4 a0 = {0.f, 0.f, 0.f, 0.f}, a1 = {0.f, 0.f, 0.f, 0.f};
; #pragma unroll
;     for (int ks = 0; ks < 4; ++ks) { a0 = mfma16(kf[0][ks], qb[ks], a0); a1 = mfma16(kf[1][ks], qb[ks], a1); }
;     __builtin_amdgcn_sched_group_barrier(0x100, 8, 0);
;     __builtin_amdgcn_sched_group_barrier(0x008, 8, 0);
; #pragma unroll
;     for (int j = 0; j < 4; ++j) {
;       if (OWN) {
;         float v0 = ((kofs + (2 * kp) * 16 + fq * 4 + j) <= qinb) ? a0[j] * scl : -INFINITY;
;         float v1 = ((kofs + (2 * kp + 1) * 16 + fq * 4 + j) <= qinb) ? a1[j] * scl : -INFINITY;
;         s[2 * kp][j] = v0; s[2 * kp + 1][j] = v1;
;         mloc = fmaxf(mloc, fmaxf(v0, v1));
;       } else {
;         s[2 * kp][j] = a0[j]; s[2 * kp + 1][j] = a1[j];
;         mloc = fmaxf(mloc, fmaxf(a0[j], a1[j]));
;       }
;     }
;   }
;   if (!OWN) mloc = lanesel ? mloc * scl : -INFINITY;
;   mloc = xq_max(mloc);
.Lmy_moba_body:
	v_add3_u32 v132, s37, v161, v162
	ds_read_b128 v[80:83], v132
	ds_read_b128 v[96:99], v132 offset:4352
	ds_read_b128 v[84:87], v132 offset:64
	ds_read_b128 v[100:103], v132 offset:4416
	ds_read_b128 v[88:91], v132 offset:128
	ds_read_b128 v[104:107], v132 offset:4480
	ds_read_b128 v[92:95], v132 offset:192
	ds_read_b128 v[108:111], v132 offset:4544
	v_cmp_lt_i32_e32 vcc, v232, v252
	s_waitcnt lgkmcnt(7)
	v_mfma_f32_16x16x32_bf16 v[80:83], v[80:83], v[32:35], 0
	s_waitcnt lgkmcnt(6)
	v_mfma_f32_16x16x32_bf16 v[96:99], v[96:99], v[32:35], 0
	s_waitcnt lgkmcnt(5)
	v_mfma_f32_16x16x32_bf16 v[80:83], v[84:87], v[36:39], v[80:83]
	s_waitcnt lgkmcnt(4)
	v_mfma_f32_16x16x32_bf16 v[84:87], v[100:103], v[36:39], v[96:99]
	s_waitcnt lgkmcnt(3)
	v_mfma_f32_16x16x32_bf16 v[80:83], v[88:91], v[40:43], v[80:83]
	s_waitcnt lgkmcnt(2)
	v_mfma_f32_16x16x32_bf16 v[84:87], v[104:107], v[40:43], v[84:87]
	s_waitcnt lgkmcnt(1)
	v_mfma_f32_16x16x32_bf16 v[100:103], v[92:95], v[44:47], v[80:83]
	s_waitcnt lgkmcnt(0)
	v_mfma_f32_16x16x32_bf16 v[96:99], v[108:111], v[44:47], v[84:87]
	ds_read_b128 v[104:107], v132 offset:13056
	s_nop 5
	ds_read_b128 v[84:87], v132 offset:8768
	v_max3_f32 v80, v100, v101, v102
	v_max3_f32 v81, v103, v96, v97
	v_max3_f32 v82, v98, v99, s79
	v_max3_f32 v120, v80, v81, v82
	ds_read_b128 v[80:83], v132 offset:8704
	ds_read_b128 v[108:111], v132 offset:13120
	ds_read_b128 v[88:91], v132 offset:8832
	ds_read_b128 v[112:115], v132 offset:13184
	ds_read_b128 v[92:95], v132 offset:8896
	ds_read_b128 v[116:119], v132 offset:13248
	s_waitcnt lgkmcnt(5)
	v_mfma_f32_16x16x32_bf16 v[80:83], v[80:83], v[32:35], 0
	v_mfma_f32_16x16x32_bf16 v[104:107], v[104:107], v[32:35], 0
	v_mfma_f32_16x16x32_bf16 v[80:83], v[84:87], v[36:39], v[80:83]
	s_waitcnt lgkmcnt(4)
	v_mfma_f32_16x16x32_bf16 v[84:87], v[108:111], v[36:39], v[104:107]
	s_waitcnt lgkmcnt(3)
	v_mfma_f32_16x16x32_bf16 v[80:83], v[88:91], v[40:43], v[80:83]
	s_waitcnt lgkmcnt(2)
	v_mfma_f32_16x16x32_bf16 v[84:87], v[112:115], v[40:43], v[84:87]
	s_waitcnt lgkmcnt(1)
	v_mfma_f32_16x16x32_bf16 v[108:111], v[92:95], v[44:47], v[80:83]
	s_waitcnt lgkmcnt(0)
	v_mfma_f32_16x16x32_bf16 v[104:107], v[116:119], v[44:47], v[84:87]
	ds_read_b128 v[112:115], v132 offset:21760
	s_nop 5
	ds_read_b128 v[84:87], v132 offset:17472
	v_max3_f32 v80, v108, v109, v110
	v_max3_f32 v81, v111, v104, v105
	v_max3_f32 v82, v106, v107, v120
	v_max3_f32 v128, v80, v81, v82
	ds_read_b128 v[80:83], v132 offset:17408
	ds_read_b128 v[116:119], v132 offset:21824
	ds_read_b128 v[88:91], v132 offset:17536
	ds_read_b128 v[120:123], v132 offset:21888
	ds_read_b128 v[92:95], v132 offset:17600
	ds_read_b128 v[124:127], v132 offset:21952
	s_waitcnt lgkmcnt(5)
	v_mfma_f32_16x16x32_bf16 v[80:83], v[80:83], v[32:35], 0
	v_mfma_f32_16x16x32_bf16 v[112:115], v[112:115], v[32:35], 0
	v_mfma_f32_16x16x32_bf16 v[80:83], v[84:87], v[36:39], v[80:83]
	s_waitcnt lgkmcnt(4)
	v_mfma_f32_16x16x32_bf16 v[84:87], v[116:119], v[36:39], v[112:115]
	s_waitcnt lgkmcnt(3)
	v_mfma_f32_16x16x32_bf16 v[80:83], v[88:91], v[40:43], v[80:83]
	s_waitcnt lgkmcnt(2)
	v_mfma_f32_16x16x32_bf16 v[84:87], v[120:123], v[40:43], v[84:87]
	s_waitcnt lgkmcnt(1)
	v_mfma_f32_16x16x32_bf16 v[112:115], v[92:95], v[44:47], v[80:83]
	s_waitcnt lgkmcnt(0)
	v_mfma_f32_16x16x32_bf16 v[124:127], v[124:127], v[44:47], v[84:87]
	ds_read_b128 v[116:119], v132 offset:30464
	s_nop 5
	ds_read_b128 v[84:87], v132 offset:26176
	v_max3_f32 v80, v112, v113, v114
	v_max3_f32 v81, v115, v124, v125
	v_max3_f32 v82, v126, v127, v128
	v_max3_f32 v136, v80, v81, v82
	ds_read_b128 v[80:83], v132 offset:26112
	ds_read_b128 v[120:123], v132 offset:30528
	ds_read_b128 v[88:91], v132 offset:26240
	ds_read_b128 v[128:131], v132 offset:30592
	ds_read_b128 v[92:95], v132 offset:26304
	ds_read_b128 v[132:135], v132 offset:30656
	s_waitcnt lgkmcnt(5)
	v_mfma_f32_16x16x32_bf16 v[80:83], v[80:83], v[32:35], 0
	v_mfma_f32_16x16x32_bf16 v[116:119], v[116:119], v[32:35], 0
	v_mfma_f32_16x16x32_bf16 v[80:83], v[84:87], v[36:39], v[80:83]
	s_waitcnt lgkmcnt(4)
	v_mfma_f32_16x16x32_bf16 v[84:87], v[120:123], v[36:39], v[116:119]
	s_waitcnt lgkmcnt(3)
	v_mfma_f32_16x16x32_bf16 v[80:83], v[88:91], v[40:43], v[80:83]
	s_waitcnt lgkmcnt(2)
	v_mfma_f32_16x16x32_bf16 v[84:87], v[128:131], v[40:43], v[84:87]
	s_waitcnt lgkmcnt(1)
	v_mfma_f32_16x16x32_bf16 v[144:147], v[92:95], v[44:47], v[80:83]
	s_waitcnt lgkmcnt(0)
	v_mfma_f32_16x16x32_bf16 v[148:151], v[132:135], v[44:47], v[84:87]
	s_nop 5
	v_max3_f32 v81, v144, v145, v146
	s_nop 0
	v_max3_f32 v82, v147, v148, v149
	v_max3_f32 v80, v136, v150, v151
	v_max3_f32 v80, v80, v81, v82
	v_mul_f32_e32 v80, 0x3e0293ee, v80
	v_cndmask_b32_e32 v81, v235, v232, vcc
	v_cndmask_b32_e64 v80, v233, v80, s[6:7]
	v_lshlrev_b32_e32 v81, 2, v81
	ds_bpermute_b32 v81, v81, v80
	v_cmp_lt_i32_e32 vcc, v226, v252
	s_waitcnt lgkmcnt(0)
	v_max_f32_e32 v81, v81, v81
	v_max_f32_e32 v80, v80, v81
	v_cndmask_b32_e32 v81, v235, v226, vcc
	v_lshlrev_b32_e32 v81, 2, v81
	ds_bpermute_b32 v81, v81, v80
	s_waitcnt lgkmcnt(0)
; DEVI unsigned pk2bf(float a, float b) { hf2 v = {a, b}; hbf2 r = __builtin_convertvector(v, hbf2); return __builtin_bit_cast(unsigned, r); }
; DEVI float xq_max(float v) { v = fmaxf(v, __shfl_xor(v, 16)); v = fmaxf(v, __shfl_xor(v, 32)); return v; }
; template <bool OWN>
; DEVI void moba_half(const u16* Kt, const u16* Vs, const int kofs, const bf16x8 (&qb)[4], f32x4 (&oacc)[8], float& m, float& lsum,
;                     const bool lanesel, const int qinb, const int lane) {
;     ...
;   if (!OWN) mloc = lanesel ? mloc * scl : -INFINITY;
;   mloc = xq_max(mloc);
;   const float mnew = fmaxf(m, mloc);
;   const float alpha = __builtin_amdgcn_exp2f(m - mnew);
;   m = mnew;
;   lsum *= alpha;
; #pragma unroll
;   for (int ct = 0; ct < 8; ++ct) { oacc[ct][0] *= alpha; oacc[ct][1] *= alpha; oacc[ct][2] *= alpha; oacc[ct][3] *= alpha; }
;   const float msub = (OWN || lanesel) ? mnew : INFINITY;
;   bf16x8 pk[4];
; #pragma unroll
;   for (int pp = 0; pp < 4; ++pp) {
;     float e[8];
; #pragma unroll
;     for (int j = 0; j < 4; ++j) {
;       if (OWN) {
;         e[j] = __builtin_amdgcn_exp2f(s[2 * pp][j] - msub);
;         e[4 + j] = __builtin_amdgcn_exp2f(s[2 * pp + 1][j] - msub);
;       } else {
;         e[j] = __builtin_amdgcn_exp2f(__builtin_fmaf(s[2 * pp][j], scl, -msub));
;         e[4 + j] = __builtin_amdgcn_exp2f(__builtin_fmaf(s[2 * pp + 1][j], scl, -msub));
;       }
;     }
;     lsum += ((e[0] + e[1]) + (e[2] + e[3])) + ((e[4] + e[5]) + (e[6] + e[7]));
;     typedef __attribute__((ext_vector_type(4))) unsigned u32x4;
;     u32x4 pw = {pk2bf(e[0], e[1]), pk2bf(e[2], e[3]), pk2bf(e[4], e[5]), pk2bf(e[6], e[7])};
;     pk[pp] = __builtin_bit_cast(bf16x8, pw);
;   }
;   const int trr = (lane & 15) >> 2, trc = lane & 3;
;   const u16* vbase = Vs + (half * 128 + fq * 4 + trr) * 144 + trc * 4;
; #pragma unroll
;   for (int cp = 0; cp < 4; ++cp) {
;     bf16x4 vf[2][8];
; #pragma unroll
;     for (int t = 0; t < 2; ++t)
; #pragma unroll
;       for (int i = 0; i < 8; ++i) vf[t][i] = tr_read(vbase + i * 16 * 144 + (2 * cp + t) * 16);
	v_max3_f32 v169, v167, v80, v81
	v_cndmask_b32_e64 v170, v233, -v169, s[6:7]
	v_fmamk_f32 v96, v96, 0x3e0293ee, v170
	v_fmamk_f32 v100, v100, 0x3e0293ee, v170
	v_exp_f32_e32 v117, v96
	v_fmamk_f32 v96, v101, 0x3e0293ee, v170
	v_fmamk_f32 v97, v97, 0x3e0293ee, v170
	v_fmamk_f32 v98, v98, 0x3e0293ee, v170
	v_exp_f32_e32 v116, v100
	v_exp_f32_e32 v96, v96
	v_exp_f32_e32 v97, v97
	v_fmamk_f32 v100, v102, 0x3e0293ee, v170
	v_exp_f32_e32 v101, v98
	v_fmamk_f32 v98, v103, 0x3e0293ee, v170
	v_fmamk_f32 v99, v99, 0x3e0293ee, v170
	v_exp_f32_e32 v100, v100
	v_exp_f32_e32 v98, v98
	v_exp_f32_e32 v99, v99
	v_pk_add_f32 v[102:103], v[116:117], v[96:97]
	v_cvt_pk_bf16_f32 v122, v117, v97
	v_fmamk_f32 v97, v104, 0x3e0293ee, v170
	v_pk_add_f32 v[118:119], v[100:101], v[98:99]
	v_cvt_pk_bf16_f32 v121, v100, v98
	v_exp_f32_e32 v98, v97
	v_fmamk_f32 v97, v109, 0x3e0293ee, v170
	v_pk_add_f32 v[102:103], v[102:103], v[118:119]
	v_exp_f32_e32 v100, v97
	v_fmamk_f32 v97, v105, 0x3e0293ee, v170
	v_pk_add_f32 v[102:103], v[102:103], v[102:103] op_sel_hi:[0,1]
	v_cvt_pk_bf16_f32 v120, v116, v96
	v_cvt_pk_bf16_f32 v123, v101, v99
	v_fmamk_f32 v96, v108, 0x3e0293ee, v170
	v_exp_f32_e32 v104, v97
	v_fmamk_f32 v97, v110, 0x3e0293ee, v170
	v_fmamk_f32 v101, v111, 0x3e0293ee, v170
	v_exp_f32_e32 v96, v96
	v_exp_f32_e32 v97, v97
	v_fmamk_f32 v99, v106, 0x3e0293ee, v170
	v_exp_f32_e32 v101, v101
	v_fmamk_f32 v102, v107, 0x3e0293ee, v170
	v_exp_f32_e32 v99, v99
	v_exp_f32_e32 v105, v102
	v_pk_add_f32 v[106:107], v[96:97], v[100:101]
	v_cvt_pk_bf16_f32 v117, v97, v101
	v_fmamk_f32 v97, v124, 0x3e0293ee, v170
	v_pk_add_f32 v[108:109], v[98:99], v[104:105]
	v_cvt_pk_bf16_f32 v118, v98, v104
	v_exp_f32_e32 v98, v97
	v_fmamk_f32 v97, v113, 0x3e0293ee, v170
	v_cvt_pk_bf16_f32 v116, v96, v100
	v_exp_f32_e32 v100, v97
	v_fmamk_f32 v97, v125, 0x3e0293ee, v170
	v_exp_f32_e32 v102, v97
	v_fmamk_f32 v97, v114, 0x3e0293ee, v170
	v_pk_add_f32 v[106:107], v[106:107], v[106:107] op_sel_hi:[0,1]
	v_exp_f32_e32 v104, v97
	v_fmamk_f32 v97, v126, 0x3e0293ee, v170
	v_pk_add_f32 v[108:109], v[108:109], v[108:109] op_sel_hi:[0,1]
	v_fmamk_f32 v96, v112, 0x3e0293ee, v170
	v_exp_f32_e32 v106, v97
	v_fmamk_f32 v97, v115, 0x3e0293ee, v170
	v_exp_f32_e32 v96, v96
	v_exp_f32_e32 v108, v97
	v_fmamk_f32 v97, v127, 0x3e0293ee, v170
	v_exp_f32_e32 v110, v97
	v_add_f32_e32 v97, v96, v100
	v_add_f32_e32 v101, v98, v102
	v_cvt_pk_bf16_f32 v124, v96, v100
	v_cvt_pk_bf16_f32 v126, v98, v102
	v_fmamk_f32 v98, v148, 0x3e0293ee, v170
	v_fmamk_f32 v100, v149, 0x3e0293ee, v170
	v_fmamk_f32 v102, v150, 0x3e0293ee, v170
	v_sub_f32_e32 v80, v167, v169
	v_cvt_pk_bf16_f32 v119, v99, v105
	v_add_f32_e32 v99, v104, v108
	v_add_f32_e32 v105, v106, v110
	v_cvt_pk_bf16_f32 v125, v104, v108
	v_cvt_pk_bf16_f32 v127, v106, v110
	v_fmamk_f32 v96, v144, 0x3e0293ee, v170
	v_exp_f32_e32 v106, v98
	v_fmamk_f32 v98, v145, 0x3e0293ee, v170
	v_exp_f32_e32 v108, v100
	v_fmamk_f32 v100, v146, 0x3e0293ee, v170
	v_exp_f32_e32 v152, v102
	v_fmamk_f32 v102, v147, 0x3e0293ee, v170
	v_exp_f32_e32 v82, v80
	v_exp_f32_e32 v96, v96
	v_exp_f32_e32 v98, v98
	v_exp_f32_e32 v100, v100
	v_exp_f32_e32 v104, v102
	v_fmac_f32_e32 v170, 0x3e0293ee, v151
	v_exp_f32_e32 v102, v170
	v_mul_f32_e32 v153, v166, v82
	v_pk_add_f32 v[110:111], v[96:97], v[98:99]
	v_pk_add_f32 v[112:113], v[100:101], v[104:105]
	v_pk_add_f32 v[114:115], v[152:153], v[102:103]
	v_pk_add_f32 v[110:111], v[110:111], v[112:113]
	v_pk_add_f32 v[112:113], v[106:107], v[108:109]
	v_pk_mul_f32 v[140:141], v[48:49], v[82:83] op_sel_hi:[1,0]
	v_pk_add_f32 v[112:113], v[112:113], v[114:115]
	v_cvt_pk_bf16_f32 v115, v152, v102
	v_pk_add_f32 v[110:111], v[110:111], v[112:113]
	v_cvt_pk_bf16_f32 v112, v96, v98
	v_lshlrev_b32_e32 v96, 1, v164
	v_add3_u32 v145, s36, v163, v96
	ds_read_b64_tr_b16 v[98:99], v145 offset:4608
	ds_read_b64_tr_b16 v[96:97], v145
	ds_read_b64_tr_b16 v[146:147], v145 offset:32
	ds_read_b64_tr_b16 v[148:149], v145 offset:4640
	v_cvt_pk_bf16_f32 v113, v100, v104
	ds_read_b64_tr_b16 v[100:101], v145 offset:9216
	ds_read_b64_tr_b16 v[102:103], v145 offset:13824
	ds_read_b64_tr_b16 v[150:151], v145 offset:9248
	ds_read_b64_tr_b16 v[152:153], v145 offset:13856
	v_pk_mul_f32 v[142:143], v[50:51], v[82:83] op_sel_hi:[1,0]
	v_pk_mul_f32 v[136:137], v[52:53], v[82:83] op_sel_hi:[1,0]
	v_pk_mul_f32 v[138:139], v[54:55], v[82:83] op_sel_hi:[1,0]
	v_cvt_pk_bf16_f32 v114, v106, v108
	ds_read_b64_tr_b16 v[104:105], v145 offset:18432
	ds_read_b64_tr_b16 v[106:107], v145 offset:23040
	ds_read_b64_tr_b16 v[170:171], v145 offset:18464
	ds_read_b64_tr_b16 v[172:173], v145 offset:23072
	v_add_f32_e32 v144, v110, v111
	ds_read_b64_tr_b16 v[108:109], v145 offset:27648
	ds_read_b64_tr_b16 v[110:111], v145 offset:32256
	ds_read_b64_tr_b16 v[174:175], v145 offset:27680
	ds_read_b64_tr_b16 v[176:177], v145 offset:32288
	s_waitcnt lgkmcnt(14)
	v_mfma_f32_16x16x32_bf16 v[96:99], v[96:99], v[120:123], v[140:143]
	v_mul_f32_e64 v132, v56, v82
	v_mul_f32_e64 v133, v57, v82
	v_pk_mul_f32 v[134:135], v[58:59], v[82:83] op_sel_hi:[1,0]
	v_pk_mul_f32 v[128:129], v[60:61], v[82:83] op_sel_hi:[1,0]
	s_waitcnt lgkmcnt(12)
	v_mfma_f32_16x16x32_bf16 v[136:139], v[146:149], v[120:123], v[136:139]
	v_mul_f32_e64 v130, v62, v82
	v_mul_f32_e64 v131, v63, v82
	v_pk_mul_f32 v[92:93], v[64:65], v[82:83] op_sel_hi:[1,0]
	v_pk_mul_f32 v[94:95], v[66:67], v[82:83] op_sel_hi:[1,0]
	s_waitcnt lgkmcnt(10)
; DEVI bf16x8 cat8(bf16x4 a, bf16x4 b) { return __builtin_shufflevector(a, b, 0, 1, 2, 3, 4, 5, 6, 7); }
; DEVI f32x4 mfma16(bf16x8 a, bf16x8 b, f32x4 c) { return __builtin_amdgcn_mfma_f32_16x16x32_bf16(a, b, c, 0, 0, 0); }
; template <bool OWN>
; DEVI void moba_half(const u16* Kt, const u16* Vs, const int kofs, const bf16x8 (&qb)[4], f32x4 (&oacc)[8], float& m, float& lsum,
;                     const bool lanesel, const int qinb, const int lane) {
;     ...
;   m = mnew;
;     ...
; #pragma unroll
;   for (int cp = 0; cp < 4; ++cp) {
;     bf16x4 vf[2][8];
; #pragma unroll
;     for (int t = 0; t < 2; ++t)
; #pragma unroll
;       for (int i = 0; i < 8; ++i) vf[t][i] = tr_read(vbase + i * 16 * 144 + (2 * cp + t) * 16);
; #pragma unroll
;     for (int pp = 0; pp < 4; ++pp) {
;       oacc[2 * cp] = mfma16(cat8(vf[0][2 * pp], vf[0][2 * pp + 1]), pk[pp], oacc[2 * cp]);
;       oacc[2 * cp + 1] = mfma16(cat8(vf[1][2 * pp], vf[1][2 * pp + 1]), pk[pp], oacc[2 * cp + 1]);
;     }
	v_mfma_f32_16x16x32_bf16 v[96:99], v[100:103], v[116:119], v[96:99]
	v_mul_f32_e64 v84, v68, v82
	v_mul_f32_e64 v85, v69, v82
	v_pk_mul_f32 v[86:87], v[70:71], v[82:83] op_sel_hi:[1,0]
	v_pk_mul_f32 v[88:89], v[72:73], v[82:83] op_sel_hi:[1,0]
	s_waitcnt lgkmcnt(8)
	v_mfma_f32_16x16x32_bf16 v[100:103], v[150:153], v[116:119], v[136:139]
	v_mul_f32_e64 v90, v74, v82
	v_mul_f32_e64 v91, v75, v82
	v_pk_mul_f32 v[80:81], v[76:77], v[82:83] op_sel_hi:[1,0]
	v_pk_mul_f32 v[82:83], v[78:79], v[82:83] op_sel_hi:[1,0]
	s_waitcnt lgkmcnt(6)
	v_mfma_f32_16x16x32_bf16 v[96:99], v[104:107], v[124:127], v[96:99]
	s_waitcnt lgkmcnt(4)
	v_mfma_f32_16x16x32_bf16 v[100:103], v[170:173], v[124:127], v[100:103]
	s_waitcnt lgkmcnt(2)
	v_mfma_f32_16x16x32_bf16 v[48:51], v[108:111], v[112:115], v[96:99]
	s_waitcnt lgkmcnt(0)
	v_mfma_f32_16x16x32_bf16 v[52:55], v[174:177], v[112:115], v[100:103]
	s_nop 1
	ds_read_b64_tr_b16 v[98:99], v145 offset:4672
	ds_read_b64_tr_b16 v[96:97], v145 offset:64
	ds_read_b64_tr_b16 v[146:147], v145 offset:96
	ds_read_b64_tr_b16 v[148:149], v145 offset:4704
	ds_read_b64_tr_b16 v[100:101], v145 offset:9280
	ds_read_b64_tr_b16 v[102:103], v145 offset:13888
	ds_read_b64_tr_b16 v[150:151], v145 offset:9312
	ds_read_b64_tr_b16 v[152:153], v145 offset:13920
	ds_read_b64_tr_b16 v[136:137], v145 offset:18496
	ds_read_b64_tr_b16 v[138:139], v145 offset:23104
	ds_read_b64_tr_b16 v[170:171], v145 offset:18528
	ds_read_b64_tr_b16 v[172:173], v145 offset:23136
	ds_read_b64_tr_b16 v[140:141], v145 offset:27712
	ds_read_b64_tr_b16 v[142:143], v145 offset:32320
	ds_read_b64_tr_b16 v[174:175], v145 offset:27744
	ds_read_b64_tr_b16 v[176:177], v145 offset:32352
	s_waitcnt lgkmcnt(14)
	v_mfma_f32_16x16x32_bf16 v[96:99], v[96:99], v[120:123], v[132:135]
	s_waitcnt lgkmcnt(12)
	v_mfma_f32_16x16x32_bf16 v[128:131], v[146:149], v[120:123], v[128:131]
	s_waitcnt lgkmcnt(10)
	v_mfma_f32_16x16x32_bf16 v[96:99], v[100:103], v[116:119], v[96:99]
	s_waitcnt lgkmcnt(8)
	v_mfma_f32_16x16x32_bf16 v[100:103], v[150:153], v[116:119], v[128:131]
	s_waitcnt lgkmcnt(6)
	v_mfma_f32_16x16x32_bf16 v[96:99], v[136:139], v[124:127], v[96:99]
	s_waitcnt lgkmcnt(4)
	v_mfma_f32_16x16x32_bf16 v[128:131], v[170:173], v[124:127], v[100:103]
	s_waitcnt lgkmcnt(2)
	v_mfma_f32_16x16x32_bf16 v[56:59], v[140:143], v[112:115], v[96:99]
	s_waitcnt lgkmcnt(0)
	v_mfma_f32_16x16x32_bf16 v[60:63], v[174:177], v[112:115], v[128:131]
	ds_read_b64_tr_b16 v[146:147], v145 offset:160
	ds_read_b64_tr_b16 v[148:149], v145 offset:4768
	ds_read_b64_tr_b16 v[132:133], v145 offset:9344
	s_nop 0
	ds_read_b64_tr_b16 v[130:131], v145 offset:4736
	ds_read_b64_tr_b16 v[128:129], v145 offset:128
	ds_read_b64_tr_b16 v[134:135], v145 offset:13952
	ds_read_b64_tr_b16 v[150:151], v145 offset:9376
	ds_read_b64_tr_b16 v[152:153], v145 offset:13984
	ds_read_b64_tr_b16 v[136:137], v145 offset:18560
	ds_read_b64_tr_b16 v[138:139], v145 offset:23168
	ds_read_b64_tr_b16 v[170:171], v145 offset:18592
	ds_read_b64_tr_b16 v[172:173], v145 offset:23200
	ds_read_b64_tr_b16 v[140:141], v145 offset:27776
	ds_read_b64_tr_b16 v[142:143], v145 offset:32384
	ds_read_b64_tr_b16 v[174:175], v145 offset:27808
	ds_read_b64_tr_b16 v[176:177], v145 offset:32416
	s_waitcnt lgkmcnt(11)
	v_mfma_f32_16x16x32_bf16 v[92:95], v[128:131], v[120:123], v[92:95]
	v_mfma_f32_16x16x32_bf16 v[84:87], v[146:149], v[120:123], v[84:87]
	s_waitcnt lgkmcnt(10)
	v_mfma_f32_16x16x32_bf16 v[92:95], v[132:135], v[116:119], v[92:95]
	s_waitcnt lgkmcnt(8)
	v_mfma_f32_16x16x32_bf16 v[84:87], v[150:153], v[116:119], v[84:87]
	s_waitcnt lgkmcnt(6)
	v_mfma_f32_16x16x32_bf16 v[92:95], v[136:139], v[124:127], v[92:95]
	s_waitcnt lgkmcnt(4)
	v_mfma_f32_16x16x32_bf16 v[84:87], v[170:173], v[124:127], v[84:87]
	s_waitcnt lgkmcnt(2)
	v_mfma_f32_16x16x32_bf16 v[64:67], v[140:143], v[112:115], v[92:95]
	s_waitcnt lgkmcnt(0)
	v_mfma_f32_16x16x32_bf16 v[68:71], v[174:177], v[112:115], v[84:87]
	ds_read_b64_tr_b16 v[130:131], v145 offset:4800
	ds_read_b64_tr_b16 v[128:129], v145 offset:192
	ds_read_b64_tr_b16 v[146:147], v145 offset:224
	ds_read_b64_tr_b16 v[148:149], v145 offset:4832
	ds_read_b64_tr_b16 v[132:133], v145 offset:9408
	ds_read_b64_tr_b16 v[134:135], v145 offset:14016
	ds_read_b64_tr_b16 v[150:151], v145 offset:9440
	ds_read_b64_tr_b16 v[152:153], v145 offset:14048
	ds_read_b64_tr_b16 v[136:137], v145 offset:18624
	ds_read_b64_tr_b16 v[138:139], v145 offset:23232
	ds_read_b64_tr_b16 v[170:171], v145 offset:18656
	ds_read_b64_tr_b16 v[172:173], v145 offset:23264
	ds_read_b64_tr_b16 v[140:141], v145 offset:27840
	ds_read_b64_tr_b16 v[142:143], v145 offset:32448
	ds_read_b64_tr_b16 v[174:175], v145 offset:27872
	ds_read_b64_tr_b16 v[176:177], v145 offset:32480
	s_waitcnt lgkmcnt(14)
	v_mfma_f32_16x16x32_bf16 v[88:91], v[128:131], v[120:123], v[88:91]
	s_waitcnt lgkmcnt(12)
	v_mfma_f32_16x16x32_bf16 v[80:83], v[146:149], v[120:123], v[80:83]
	s_waitcnt lgkmcnt(10)
	v_mfma_f32_16x16x32_bf16 v[88:91], v[132:135], v[116:119], v[88:91]
	s_waitcnt lgkmcnt(8)
	v_mfma_f32_16x16x32_bf16 v[80:83], v[150:153], v[116:119], v[80:83]
	s_waitcnt lgkmcnt(6)
	v_mfma_f32_16x16x32_bf16 v[88:91], v[136:139], v[124:127], v[88:91]
	s_waitcnt lgkmcnt(4)
	v_mfma_f32_16x16x32_bf16 v[80:83], v[170:173], v[124:127], v[80:83]
	s_waitcnt lgkmcnt(2)
	v_mfma_f32_16x16x32_bf16 v[72:75], v[140:143], v[112:115], v[88:91]
	s_waitcnt lgkmcnt(0)
	v_mfma_f32_16x16x32_bf16 v[76:79], v[174:177], v[112:115], v[80:83]
	v_mov_b32_e32 v166, v144
	v_mov_b32_e32 v167, v169

; DEVI void moba_item(const Params& p, int l, int item) {
;     ...
;     if (nblk >= 0) {
; #pragma unroll
;       for (int i = 0; i < 4; ++i) {
;         *(bf16x8*)(Kn + (kkey + 32 * i) * 136 + kdg * 8) = pk_[i];
;         *(bf16x8*)(Vn + (kkey + 32 * i) * 144 + kdg * 8) = pv_[i];
;       }
;       MOBA_NEXT(nblk, nhalf, n2blk, n2half);
;       if (n2blk >= 0) MOBA_LOAD(n2blk, n2half);
.Lmy_moba_658:
	s_and_b64 s[6:7], s[2:3], exec
	s_cselect_b32 s6, s72, s78
	s_cselect_b32 s7, s70, 0
	s_cmp_eq_u32 s35, s28
	v_add3_u32 v178, s7, v199, v155
	v_add3_u32 v179, s6, v210, v159
	s_cselect_b64 s[6:7], -1, 0
	s_and_b64 s[6:7], s[8:9], s[6:7]
	s_waitcnt vmcnt(7)
	ds_write_b128 v178, v[0:3]
	s_waitcnt vmcnt(6)
	ds_write_b128 v179, v[4:7]
	s_waitcnt vmcnt(5)
	ds_write_b128 v178, v[8:11] offset:8704
	s_waitcnt vmcnt(4)
	ds_write_b128 v179, v[12:15] offset:9216
	s_waitcnt vmcnt(3)
	ds_write_b128 v178, v[16:19] offset:17408
	s_waitcnt vmcnt(2)
	ds_write_b128 v179, v[20:23] offset:18432
	s_waitcnt vmcnt(1)
	ds_write_b128 v178, v[24:27] offset:26112
	s_waitcnt vmcnt(0)
	ds_write_b128 v179, v[28:31] offset:27648
	s_or_b64 s[6:7], s[10:11], s[6:7]
	v_sub_co_u32_e64 v178, s[22:23], s30, 1
	s_ff1_i32_b32 s34, s30
	s_and_b64 s[22:23], s[22:23], exec
	s_cselect_b32 s34, -1, s34
	s_and_b64 s[22:23], s[6:7], exec
	v_readfirstlane_b32 s22, v178
	s_cselect_b32 s23, s34, s35
	s_cselect_b32 s22, s22, -1
	s_cmp_lt_i32 s23, 0
	s_mov_b32 s34, -1
	s_cbranch_scc1 .Lmy_moba_660
	s_lshl_b32 s34, s23, 8
	s_add_i32 s34, s34, s29
	s_and_b64 s[36:37], s[6:7], exec
	s_cselect_b32 s36, 0, 0x80
	s_or_b32 s34, s34, s36
	v_or_b32_e32 v26, s34, v154
	v_mov_b64_e32 v[24:25], s[92:93]
	v_mad_u64_u32 v[0:1], s[36:37], v26, s97, v[24:25]
	v_lshl_add_u64 v[0:1], v[0:1], 0, s[98:99]
	v_or_b32_e32 v8, 32, v26
	v_lshl_add_u64 v[0:1], v[0:1], 0, v[210:211]
	v_mad_u64_u32 v[8:9], s[36:37], v8, s97, v[24:25]
	v_add_co_u32_e32 v4, vcc, s68, v0
	v_lshl_add_u64 v[8:9], v[8:9], 0, s[98:99]
	v_or_b32_e32 v16, 64, v26
	v_addc_co_u32_e32 v5, vcc, 0, v1, vcc
	v_lshl_add_u64 v[8:9], v[8:9], 0, v[210:211]
	v_mad_u64_u32 v[16:17], s[36:37], v16, s97, v[24:25]
	v_add_co_u32_e32 v12, vcc, s68, v8
	v_lshl_add_u64 v[16:17], v[16:17], 0, s[98:99]
	v_or_b32_e32 v26, 0x60, v26
	v_addc_co_u32_e32 v13, vcc, 0, v9, vcc
	v_lshl_add_u64 v[16:17], v[16:17], 0, v[210:211]
	v_mad_u64_u32 v[24:25], s[36:37], v26, s97, v[24:25]
	v_add_co_u32_e32 v20, vcc, s68, v16
	v_lshl_add_u64 v[24:25], v[24:25], 0, s[98:99]
	s_nop 0
	v_addc_co_u32_e32 v21, vcc, 0, v17, vcc
	v_lshl_add_u64 v[24:25], v[24:25], 0, v[210:211]
	v_add_co_u32_e32 v28, vcc, 0x3000, v24
	global_load_dwordx4 v[0:3], v[4:5], off offset:512
	s_nop 0
	global_load_dwordx4 v[4:7], v[4:5], off offset:2560
	v_addc_co_u32_e32 v29, vcc, 0, v25, vcc
	global_load_dwordx4 v[8:11], v[12:13], off offset:512
	s_nop 0
	global_load_dwordx4 v[12:15], v[12:13], off offset:2560
	s_nop 0
	global_load_dwordx4 v[16:19], v[20:21], off offset:512
	s_nop 0
	global_load_dwordx4 v[20:23], v[20:21], off offset:2560
	s_nop 0
	global_load_dwordx4 v[24:27], v[28:29], off offset:512
	s_nop 0
	global_load_dwordx4 v[28:31], v[28:29], off offset:2560
	s_mov_b32 s34, s23
